# phase 0: fifth transpose item of workgroups 0..31 moved to workgroups 224..255, no duplicate last item
# speedup vs baseline: 1.0081x; 1.0081x over previous
.Lp0t_entry:
	v_readlane_b32 s80, v254, 38
	v_readlane_b32 s81, v254, 39
	v_readlane_b32 s82, v254, 48
	v_readlane_b32 s83, v254, 49
	s_nop 3
	s_mov_b32 s85, s21
	s_mov_b32 s86, s12
	s_cmpk_gt_i32 s86, 0x3ff
	s_cbranch_scc1 .LBB0_726
	s_mov_b32 s84, s86
.Lp0t_klast:
	s_add_u32 s0, s84, s85
	s_cmpk_gt_u32 s0, 0x3ff
	s_cbranch_scc1 .Lp0t_kdone
	s_mov_b32 s84, s0
	s_branch .Lp0t_klast
.Lp0t_kdone:
	v_lshrrev_b32_e32 v112, 4, v1
	v_and_b32_e32 v113, 15, v1
	v_lshlrev_b32_e32 v113, 4, v113
	v_mul_u32_u24_e32 v114, 0x104, v112
	v_add_u32_e32 v114, v114, v113
	v_lshrrev_b32_e32 v116, 3, v1
	v_and_b32_e32 v117, 7, v1
	v_mul_u32_u24_e32 v115, 0x1040, v117
	v_lshl_add_u32 v115, v116, 2, v115
	v_lshlrev_b32_e32 v117, 5, v117
	s_mul_i32 s48, s85, 0
	s_add_u32 s48, s48, s86
	s_min_u32 s48, s48, s84
	s_sub_u32 s0, s48, 0xe0
	s_mul_i32 s2, s0, 0x4ed
	s_lshr_b32 s2, s2, 17
	s_mul_i32 s3, s2, 0x68
	s_sub_u32 s3, s0, s3
	s_mul_i32 s4, s2, 0x340000
	s_lshl_b32 s0, s3, 8
	s_add_u32 s4, s4, s0
	s_add_u32 s6, s80, s4
	s_addc_u32 s7, s81, 0
	s_lshl_b32 s4, s3, 17
	s_lshl_b32 s0, s2, 8
	s_add_u32 s4, s4, s0
	s_add_u32 s8, s82, s4
	s_addc_u32 s9, s83, 0
	s_movk_i32 s10, 0x6800
	s_movk_i32 s11, 0x800
	v_mul_lo_u32 v123, v112, s10
	v_add_u32_e32 v118, v123, v113
	s_lshl_b32 vcc_lo, s10, 5
	v_add_u32_e32 v119, vcc_lo, v118
	v_add_u32_e32 v120, vcc_lo, v119
	v_add_u32_e32 v121, vcc_lo, v120
	global_load_dwordx4 v[40:43], v118, s[6:7]
	global_load_dwordx4 v[44:47], v119, s[6:7]
	global_load_dwordx4 v[48:51], v120, s[6:7]
	global_load_dwordx4 v[52:55], v121, s[6:7]
	s_mul_i32 s48, s85, 1
	s_add_u32 s48, s48, s86
	s_min_u32 s48, s48, s84
	s_sub_u32 s0, s48, 0xe0
	s_mul_i32 s2, s0, 0x4ed
	s_lshr_b32 s2, s2, 17
	s_mul_i32 s3, s2, 0x68
	s_sub_u32 s3, s0, s3
	s_mul_i32 s4, s2, 0x340000
	s_lshl_b32 s0, s3, 8
	s_add_u32 s4, s4, s0
	s_add_u32 s6, s80, s4
	s_addc_u32 s7, s81, 0
	s_lshl_b32 s4, s3, 17
	s_lshl_b32 s0, s2, 8
	s_add_u32 s4, s4, s0
	s_add_u32 s8, s82, s4
	s_addc_u32 s9, s83, 0
	s_movk_i32 s10, 0x6800
	s_movk_i32 s11, 0x800
	v_mul_lo_u32 v123, v112, s10
	v_add_u32_e32 v118, v123, v113
	s_lshl_b32 vcc_lo, s10, 5
	v_add_u32_e32 v119, vcc_lo, v118
	v_add_u32_e32 v120, vcc_lo, v119
	v_add_u32_e32 v121, vcc_lo, v120
	global_load_dwordx4 v[56:59], v118, s[6:7]
	global_load_dwordx4 v[60:63], v119, s[6:7]
	global_load_dwordx4 v[64:67], v120, s[6:7]
	global_load_dwordx4 v[68:71], v121, s[6:7]
	s_mul_i32 s48, s85, 2
	s_add_u32 s48, s48, s86
	s_min_u32 s48, s48, s84
	s_sub_u32 s0, s48, 0xe0
	s_mul_i32 s2, s0, 0x4ed
	s_lshr_b32 s2, s2, 17
	s_mul_i32 s3, s2, 0x68
	s_sub_u32 s3, s0, s3
	s_mul_i32 s4, s2, 0x340000
	s_lshl_b32 s0, s3, 8
	s_add_u32 s4, s4, s0
	s_add_u32 s6, s80, s4
	s_addc_u32 s7, s81, 0
	s_lshl_b32 s4, s3, 17
	s_lshl_b32 s0, s2, 8
	s_add_u32 s4, s4, s0
	s_add_u32 s8, s82, s4
	s_addc_u32 s9, s83, 0
	s_movk_i32 s10, 0x6800
	s_movk_i32 s11, 0x800
	v_mul_lo_u32 v123, v112, s10
	v_add_u32_e32 v118, v123, v113
	s_lshl_b32 vcc_lo, s10, 5
	v_add_u32_e32 v119, vcc_lo, v118
	v_add_u32_e32 v120, vcc_lo, v119
	v_add_u32_e32 v121, vcc_lo, v120
	global_load_dwordx4 v[72:75], v118, s[6:7]
	global_load_dwordx4 v[76:79], v119, s[6:7]
	global_load_dwordx4 v[80:83], v120, s[6:7]
	global_load_dwordx4 v[84:87], v121, s[6:7]
	s_waitcnt vmcnt(8)
	ds_write_b32 v114, v40 offset:0
	ds_write_b32 v114, v41 offset:4
	ds_write_b32 v114, v42 offset:8
	ds_write_b32 v114, v43 offset:12
	ds_write_b32 v114, v44 offset:8320
	ds_write_b32 v114, v45 offset:8324
	ds_write_b32 v114, v46 offset:8328
	ds_write_b32 v114, v47 offset:8332
	ds_write_b32 v114, v48 offset:16640
	ds_write_b32 v114, v49 offset:16644
	ds_write_b32 v114, v50 offset:16648
	ds_write_b32 v114, v51 offset:16652
	ds_write_b32 v114, v52 offset:24960
	ds_write_b32 v114, v53 offset:24964
	ds_write_b32 v114, v54 offset:24968
	ds_write_b32 v114, v55 offset:24972
	s_waitcnt lgkmcnt(0)
	s_barrier
	ds_read_b32 v88, v115 offset:0
	ds_read_b32 v89, v115 offset:260
	ds_read_b32 v90, v115 offset:520
	ds_read_b32 v91, v115 offset:780
	ds_read_b32 v92, v115 offset:1040
	ds_read_b32 v93, v115 offset:1300
	ds_read_b32 v94, v115 offset:1560
	ds_read_b32 v95, v115 offset:1820
	ds_read_b32 v96, v115 offset:2080
	ds_read_b32 v97, v115 offset:2340
	ds_read_b32 v98, v115 offset:2600
	ds_read_b32 v99, v115 offset:2860
	ds_read_b32 v100, v115 offset:3120
	ds_read_b32 v101, v115 offset:3380
	ds_read_b32 v102, v115 offset:3640
	ds_read_b32 v103, v115 offset:3900
	s_mul_i32 s48, s85, 0
	s_add_u32 s48, s48, s86
	s_min_u32 s48, s48, s84
	s_sub_u32 s0, s48, 0xe0
	s_mul_i32 s2, s0, 0x4ed
	s_lshr_b32 s2, s2, 17
	s_mul_i32 s3, s2, 0x68
	s_sub_u32 s3, s0, s3
	s_mul_i32 s4, s2, 0x340000
	s_lshl_b32 s0, s3, 8
	s_add_u32 s4, s4, s0
	s_add_u32 s6, s80, s4
	s_addc_u32 s7, s81, 0
	s_lshl_b32 s4, s3, 17
	s_lshl_b32 s0, s2, 8
	s_add_u32 s4, s4, s0
	s_add_u32 s8, s82, s4
	s_addc_u32 s9, s83, 0
	s_movk_i32 s10, 0x6800
	s_movk_i32 s11, 0x800
	v_mul_lo_u32 v122, v116, s11
	v_add_u32_e32 v122, v122, v117
	s_waitcnt lgkmcnt(0)
	v_cvt_pk_bf16_f32 v104, v88, v89
	v_cvt_pk_bf16_f32 v105, v90, v91
	v_cvt_pk_bf16_f32 v106, v92, v93
	v_cvt_pk_bf16_f32 v107, v94, v95
	v_cvt_pk_bf16_f32 v108, v96, v97
	v_cvt_pk_bf16_f32 v109, v98, v99
	v_cvt_pk_bf16_f32 v110, v100, v101
	v_cvt_pk_bf16_f32 v111, v102, v103
	global_store_dwordx4 v122, v[104:107], s[8:9]
	global_store_dwordx4 v122, v[108:111], s[8:9] offset:16
	s_nop 1
	s_mul_i32 s48, s85, 1
	s_add_u32 s48, s48, s86
	s_cmp_gt_u32 s48, s84
	s_cbranch_scc1 .Lp0t_alldone
	s_mul_i32 s48, s85, 3
	s_add_u32 s48, s48, s86
	s_min_u32 s48, s48, s84
	s_sub_u32 s0, s48, 0xe0
	s_mul_i32 s2, s0, 0x4ed
	s_lshr_b32 s2, s2, 17
	s_mul_i32 s3, s2, 0x68
	s_sub_u32 s3, s0, s3
	s_mul_i32 s4, s2, 0x340000
	s_lshl_b32 s0, s3, 8
	s_add_u32 s4, s4, s0
	s_add_u32 s6, s80, s4
	s_addc_u32 s7, s81, 0
	s_lshl_b32 s4, s3, 17
	s_lshl_b32 s0, s2, 8
	s_add_u32 s4, s4, s0
	s_add_u32 s8, s82, s4
	s_addc_u32 s9, s83, 0
	s_movk_i32 s10, 0x6800
	s_movk_i32 s11, 0x800
	v_mul_lo_u32 v123, v112, s10
	v_add_u32_e32 v118, v123, v113
	s_lshl_b32 vcc_lo, s10, 5
	v_add_u32_e32 v119, vcc_lo, v118
	v_add_u32_e32 v120, vcc_lo, v119
	v_add_u32_e32 v121, vcc_lo, v120
	global_load_dwordx4 v[40:43], v118, s[6:7]
	global_load_dwordx4 v[44:47], v119, s[6:7]
	global_load_dwordx4 v[48:51], v120, s[6:7]
	global_load_dwordx4 v[52:55], v121, s[6:7]
	s_waitcnt vmcnt(10)
	ds_write_b32 v114, v56 offset:33792
	ds_write_b32 v114, v57 offset:33796
	ds_write_b32 v114, v58 offset:33800
	ds_write_b32 v114, v59 offset:33804
	ds_write_b32 v114, v60 offset:42112
	ds_write_b32 v114, v61 offset:42116
	ds_write_b32 v114, v62 offset:42120
	ds_write_b32 v114, v63 offset:42124
	ds_write_b32 v114, v64 offset:50432
	ds_write_b32 v114, v65 offset:50436
	ds_write_b32 v114, v66 offset:50440
	ds_write_b32 v114, v67 offset:50444
	ds_write_b32 v114, v68 offset:58752
	ds_write_b32 v114, v69 offset:58756
	ds_write_b32 v114, v70 offset:58760
	ds_write_b32 v114, v71 offset:58764
	s_waitcnt lgkmcnt(0)
	s_barrier
	ds_read_b32 v88, v115 offset:33792
	ds_read_b32 v89, v115 offset:34052
	ds_read_b32 v90, v115 offset:34312
	ds_read_b32 v91, v115 offset:34572
	ds_read_b32 v92, v115 offset:34832
	ds_read_b32 v93, v115 offset:35092
	ds_read_b32 v94, v115 offset:35352
	ds_read_b32 v95, v115 offset:35612
	ds_read_b32 v96, v115 offset:35872
	ds_read_b32 v97, v115 offset:36132
	ds_read_b32 v98, v115 offset:36392
	ds_read_b32 v99, v115 offset:36652
	ds_read_b32 v100, v115 offset:36912
	ds_read_b32 v101, v115 offset:37172
	ds_read_b32 v102, v115 offset:37432
	ds_read_b32 v103, v115 offset:37692
	s_mul_i32 s48, s85, 1
	s_add_u32 s48, s48, s86
	s_min_u32 s48, s48, s84
	s_sub_u32 s0, s48, 0xe0
	s_mul_i32 s2, s0, 0x4ed
	s_lshr_b32 s2, s2, 17
	s_mul_i32 s3, s2, 0x68
	s_sub_u32 s3, s0, s3
	s_mul_i32 s4, s2, 0x340000
	s_lshl_b32 s0, s3, 8
	s_add_u32 s4, s4, s0
	s_add_u32 s6, s80, s4
	s_addc_u32 s7, s81, 0
	s_lshl_b32 s4, s3, 17
	s_lshl_b32 s0, s2, 8
	s_add_u32 s4, s4, s0
	s_add_u32 s8, s82, s4
	s_addc_u32 s9, s83, 0
	s_movk_i32 s10, 0x6800
	s_movk_i32 s11, 0x800
	v_mul_lo_u32 v122, v116, s11
	v_add_u32_e32 v122, v122, v117
	s_waitcnt lgkmcnt(0)
	v_cvt_pk_bf16_f32 v104, v88, v89
	v_cvt_pk_bf16_f32 v105, v90, v91
	v_cvt_pk_bf16_f32 v106, v92, v93
	v_cvt_pk_bf16_f32 v107, v94, v95
	v_cvt_pk_bf16_f32 v108, v96, v97
	v_cvt_pk_bf16_f32 v109, v98, v99
	v_cvt_pk_bf16_f32 v110, v100, v101
	v_cvt_pk_bf16_f32 v111, v102, v103
	global_store_dwordx4 v122, v[104:107], s[8:9]
	global_store_dwordx4 v122, v[108:111], s[8:9] offset:16
	s_nop 1
	s_mul_i32 s48, s85, 2
	s_add_u32 s48, s48, s86
	s_cmp_gt_u32 s48, s84
	s_cbranch_scc1 .Lp0t_alldone
	s_add_u32 s48, s86, 0x320
	s_sub_u32 s0, s48, 0xe0
	s_mul_i32 s2, s0, 0x4ed
	s_lshr_b32 s2, s2, 17
	s_mul_i32 s3, s2, 0x68
	s_sub_u32 s3, s0, s3
	s_mul_i32 s4, s2, 0x340000
	s_lshl_b32 s0, s3, 8
	s_add_u32 s4, s4, s0
	s_add_u32 s6, s80, s4
	s_addc_u32 s7, s81, 0
	s_lshl_b32 s4, s3, 17
	s_lshl_b32 s0, s2, 8
	s_add_u32 s4, s4, s0
	s_add_u32 s8, s82, s4
	s_addc_u32 s9, s83, 0
	s_movk_i32 s10, 0x6800
	s_movk_i32 s11, 0x800
	v_mul_lo_u32 v123, v112, s10
	v_add_u32_e32 v118, v123, v113
	s_lshl_b32 vcc_lo, s10, 5
	v_add_u32_e32 v119, vcc_lo, v118
	v_add_u32_e32 v120, vcc_lo, v119
	v_add_u32_e32 v121, vcc_lo, v120
	global_load_dwordx4 v[56:59], v118, s[6:7]
	global_load_dwordx4 v[60:63], v119, s[6:7]
	global_load_dwordx4 v[64:67], v120, s[6:7]
	global_load_dwordx4 v[68:71], v121, s[6:7]
	s_waitcnt vmcnt(12)
	ds_write_b32 v114, v72 offset:0
	ds_write_b32 v114, v73 offset:4
	ds_write_b32 v114, v74 offset:8
	ds_write_b32 v114, v75 offset:12
	ds_write_b32 v114, v76 offset:8320
	ds_write_b32 v114, v77 offset:8324
	ds_write_b32 v114, v78 offset:8328
	ds_write_b32 v114, v79 offset:8332
	ds_write_b32 v114, v80 offset:16640
	ds_write_b32 v114, v81 offset:16644
	ds_write_b32 v114, v82 offset:16648
	ds_write_b32 v114, v83 offset:16652
	ds_write_b32 v114, v84 offset:24960
	ds_write_b32 v114, v85 offset:24964
	ds_write_b32 v114, v86 offset:24968
	ds_write_b32 v114, v87 offset:24972
	s_waitcnt lgkmcnt(0)
	s_barrier
	ds_read_b32 v88, v115 offset:0
	ds_read_b32 v89, v115 offset:260
	ds_read_b32 v90, v115 offset:520
	ds_read_b32 v91, v115 offset:780
	ds_read_b32 v92, v115 offset:1040
	ds_read_b32 v93, v115 offset:1300
	ds_read_b32 v94, v115 offset:1560
	ds_read_b32 v95, v115 offset:1820
	ds_read_b32 v96, v115 offset:2080
	ds_read_b32 v97, v115 offset:2340
	ds_read_b32 v98, v115 offset:2600
	ds_read_b32 v99, v115 offset:2860
	ds_read_b32 v100, v115 offset:3120
	ds_read_b32 v101, v115 offset:3380
	ds_read_b32 v102, v115 offset:3640
	ds_read_b32 v103, v115 offset:3900
	s_mul_i32 s48, s85, 2
	s_add_u32 s48, s48, s86
	s_min_u32 s48, s48, s84
	s_sub_u32 s0, s48, 0xe0
	s_mul_i32 s2, s0, 0x4ed
	s_lshr_b32 s2, s2, 17
	s_mul_i32 s3, s2, 0x68
	s_sub_u32 s3, s0, s3
	s_mul_i32 s4, s2, 0x340000
	s_lshl_b32 s0, s3, 8
	s_add_u32 s4, s4, s0
	s_add_u32 s6, s80, s4
	s_addc_u32 s7, s81, 0
	s_lshl_b32 s4, s3, 17
	s_lshl_b32 s0, s2, 8
	s_add_u32 s4, s4, s0
	s_add_u32 s8, s82, s4
	s_addc_u32 s9, s83, 0
	s_movk_i32 s10, 0x6800
	s_movk_i32 s11, 0x800
	v_mul_lo_u32 v122, v116, s11
	v_add_u32_e32 v122, v122, v117
	s_waitcnt lgkmcnt(0)
	v_cvt_pk_bf16_f32 v104, v88, v89
	v_cvt_pk_bf16_f32 v105, v90, v91
	v_cvt_pk_bf16_f32 v106, v92, v93
	v_cvt_pk_bf16_f32 v107, v94, v95
	v_cvt_pk_bf16_f32 v108, v96, v97
	v_cvt_pk_bf16_f32 v109, v98, v99
	v_cvt_pk_bf16_f32 v110, v100, v101
	v_cvt_pk_bf16_f32 v111, v102, v103
	global_store_dwordx4 v122, v[104:107], s[8:9]
	global_store_dwordx4 v122, v[108:111], s[8:9] offset:16
	s_nop 1
	s_mul_i32 s48, s85, 3
	s_add_u32 s48, s48, s86
	s_cmp_gt_u32 s48, s84
	s_cbranch_scc1 .Lp0t_alldone
	s_waitcnt vmcnt(8)
	ds_write_b32 v114, v40 offset:33792
	ds_write_b32 v114, v41 offset:33796
	ds_write_b32 v114, v42 offset:33800
	ds_write_b32 v114, v43 offset:33804
	ds_write_b32 v114, v44 offset:42112
	ds_write_b32 v114, v45 offset:42116
	ds_write_b32 v114, v46 offset:42120
	ds_write_b32 v114, v47 offset:42124
	ds_write_b32 v114, v48 offset:50432
	ds_write_b32 v114, v49 offset:50436
	ds_write_b32 v114, v50 offset:50440
	ds_write_b32 v114, v51 offset:50444
	ds_write_b32 v114, v52 offset:58752
	ds_write_b32 v114, v53 offset:58756
	ds_write_b32 v114, v54 offset:58760
	ds_write_b32 v114, v55 offset:58764
	s_waitcnt lgkmcnt(0)
	s_barrier
	ds_read_b32 v88, v115 offset:33792
	ds_read_b32 v89, v115 offset:34052
	ds_read_b32 v90, v115 offset:34312
	ds_read_b32 v91, v115 offset:34572
	ds_read_b32 v92, v115 offset:34832
	ds_read_b32 v93, v115 offset:35092
	ds_read_b32 v94, v115 offset:35352
	ds_read_b32 v95, v115 offset:35612
	ds_read_b32 v96, v115 offset:35872
	ds_read_b32 v97, v115 offset:36132
	ds_read_b32 v98, v115 offset:36392
	ds_read_b32 v99, v115 offset:36652
	ds_read_b32 v100, v115 offset:36912
	ds_read_b32 v101, v115 offset:37172
	ds_read_b32 v102, v115 offset:37432
	ds_read_b32 v103, v115 offset:37692
	s_mul_i32 s48, s85, 3
	s_add_u32 s48, s48, s86
	s_min_u32 s48, s48, s84
	s_sub_u32 s0, s48, 0xe0
	s_mul_i32 s2, s0, 0x4ed
	s_lshr_b32 s2, s2, 17
	s_mul_i32 s3, s2, 0x68
	s_sub_u32 s3, s0, s3
	s_mul_i32 s4, s2, 0x340000
	s_lshl_b32 s0, s3, 8
	s_add_u32 s4, s4, s0
	s_add_u32 s6, s80, s4
	s_addc_u32 s7, s81, 0
	s_lshl_b32 s4, s3, 17
	s_lshl_b32 s0, s2, 8
	s_add_u32 s4, s4, s0
	s_add_u32 s8, s82, s4
	s_addc_u32 s9, s83, 0
	s_movk_i32 s10, 0x6800
	s_movk_i32 s11, 0x800
	v_mul_lo_u32 v122, v116, s11
	v_add_u32_e32 v122, v122, v117
	s_waitcnt lgkmcnt(0)
	v_cvt_pk_bf16_f32 v104, v88, v89
	v_cvt_pk_bf16_f32 v105, v90, v91
	v_cvt_pk_bf16_f32 v106, v92, v93
	v_cvt_pk_bf16_f32 v107, v94, v95
	v_cvt_pk_bf16_f32 v108, v96, v97
	v_cvt_pk_bf16_f32 v109, v98, v99
	v_cvt_pk_bf16_f32 v110, v100, v101
	v_cvt_pk_bf16_f32 v111, v102, v103
	global_store_dwordx4 v122, v[104:107], s[8:9]
	global_store_dwordx4 v122, v[108:111], s[8:9] offset:16
	s_nop 1
	s_cmpk_lt_u32 s86, 0xe0
	s_cbranch_scc1 .Lp0t_alldone
	s_cmpk_gt_u32 s86, 0xff
	s_cbranch_scc1 .Lp0t_alldone
	s_waitcnt vmcnt(4)
	ds_write_b32 v114, v56 offset:0
	ds_write_b32 v114, v57 offset:4
	ds_write_b32 v114, v58 offset:8
	ds_write_b32 v114, v59 offset:12
	ds_write_b32 v114, v60 offset:8320
	ds_write_b32 v114, v61 offset:8324
	ds_write_b32 v114, v62 offset:8328
	ds_write_b32 v114, v63 offset:8332
	ds_write_b32 v114, v64 offset:16640
	ds_write_b32 v114, v65 offset:16644
	ds_write_b32 v114, v66 offset:16648
	ds_write_b32 v114, v67 offset:16652
	ds_write_b32 v114, v68 offset:24960
	ds_write_b32 v114, v69 offset:24964
	ds_write_b32 v114, v70 offset:24968
	ds_write_b32 v114, v71 offset:24972
	s_waitcnt lgkmcnt(0)
	s_barrier
	ds_read_b32 v88, v115 offset:0
	ds_read_b32 v89, v115 offset:260
	ds_read_b32 v90, v115 offset:520
	ds_read_b32 v91, v115 offset:780
	ds_read_b32 v92, v115 offset:1040
	ds_read_b32 v93, v115 offset:1300
	ds_read_b32 v94, v115 offset:1560
	ds_read_b32 v95, v115 offset:1820
	ds_read_b32 v96, v115 offset:2080
	ds_read_b32 v97, v115 offset:2340
	ds_read_b32 v98, v115 offset:2600
	ds_read_b32 v99, v115 offset:2860
	ds_read_b32 v100, v115 offset:3120
	ds_read_b32 v101, v115 offset:3380
	ds_read_b32 v102, v115 offset:3640
	ds_read_b32 v103, v115 offset:3900
	s_add_u32 s48, s86, 0x320
	s_sub_u32 s0, s48, 0xe0
	s_mul_i32 s2, s0, 0x4ed
	s_lshr_b32 s2, s2, 17
	s_mul_i32 s3, s2, 0x68
	s_sub_u32 s3, s0, s3
	s_mul_i32 s4, s2, 0x340000
	s_lshl_b32 s0, s3, 8
	s_add_u32 s4, s4, s0
	s_add_u32 s6, s80, s4
	s_addc_u32 s7, s81, 0
	s_lshl_b32 s4, s3, 17
	s_lshl_b32 s0, s2, 8
	s_add_u32 s4, s4, s0
	s_add_u32 s8, s82, s4
	s_addc_u32 s9, s83, 0
	s_movk_i32 s10, 0x6800
	s_movk_i32 s11, 0x800
	v_mul_lo_u32 v122, v116, s11
	v_add_u32_e32 v122, v122, v117
	s_waitcnt lgkmcnt(0)
	v_cvt_pk_bf16_f32 v104, v88, v89
	v_cvt_pk_bf16_f32 v105, v90, v91
	v_cvt_pk_bf16_f32 v106, v92, v93
	v_cvt_pk_bf16_f32 v107, v94, v95
	v_cvt_pk_bf16_f32 v108, v96, v97
	v_cvt_pk_bf16_f32 v109, v98, v99
	v_cvt_pk_bf16_f32 v110, v100, v101
	v_cvt_pk_bf16_f32 v111, v102, v103
	global_store_dwordx4 v122, v[104:107], s[8:9]
	global_store_dwordx4 v122, v[108:111], s[8:9] offset:16
	s_nop 1
.Lp0t_alldone:
	s_waitcnt vmcnt(0)
	s_barrier
	s_branch .LBB0_726
